# layer boundary GEMM5>GEMM1 XCD-local too: last-arriving workgroup of each group writes the L2 back once and raises a flag the neighbour group waits on (11 of 14 local; mixer>GEMM2 stays full)
# speedup vs baseline: 1.0052x; 1.0052x over previous
; __device__ __forceinline__ unsigned xb_ld(unsigned* p)              { return __hip_atomic_load(p, __ATOMIC_RELAXED, __HIP_MEMORY_SCOPE_AGENT); }
; __device__ __forceinline__ unsigned xb_add(unsigned* p, unsigned v) { return __hip_atomic_fetch_add(p, v, __ATOMIC_RELAXED, __HIP_MEMORY_SCOPE_AGENT); }
; #define XB_SPIN(cond, bar) do { unsigned _sp = 0; while (cond) { __builtin_amdgcn_s_sleep(1); \
;     if ((++_sp & 255u) == 0u) { if (xb_ld(&(bar)[XB_TMO])) break; if (_sp > XB_SPIN_CAP) { atomicAdd(&(bar)[XB_TMO], 1u); break; } } } } while (0)
; __device__ __forceinline__ void xcd_barrier(const XcdBarrier& b) {
;     asm volatile("s_waitcnt vmcnt(0)" ::: "memory");
;     __syncthreads();
;     if (threadIdx.x == 0) {
;         unsigned* bar = b.bar;
;         __builtin_amdgcn_s_waitcnt(0);
;         unsigned nloc = b.st[0], nx = b.st[1];
;         if (nloc == 0u) { xcd_barrier_complete(bar, b.x, nloc, nx); b.st[0] = nloc; b.st[1] = nx; }
;         const unsigned old = xb_add(&bar[XB_XSUB(b.x)], 1u);
;         const unsigned gen = old / nloc;
;         if (old + 1u == (gen + 1u) * nloc) {
;             __builtin_amdgcn_fence(__ATOMIC_RELEASE, "agent");
;             asm volatile("s_waitcnt vmcnt(0)" ::: "memory");
;             const unsigned og = xb_add(&bar[XB_TOP], 1u);
;             const unsigned tg = og / nx;
;             if (og + 1u == (tg + 1u) * nx) xb_add(&bar[XB_TOPGEN], 1u);
;             else XB_SPIN(xb_ld(&bar[XB_TOPGEN]) == tg, bar);
;             __builtin_amdgcn_fence(__ATOMIC_ACQUIRE, "agent");
;             xb_add(&bar[XB_XGEN(b.x)], 1u);
;             asm volatile("s_waitcnt vmcnt(0)" ::: "memory");
;         } else {
;             XB_SPIN(xb_ld(&bar[XB_XGEN(b.x)]) == gen, bar);
;             __builtin_amdgcn_fence(__ATOMIC_ACQUIRE, "agent");
;             asm volatile("s_waitcnt vmcnt(0)" ::: "memory");
;         }
;     }
;     __syncthreads();
; }
cvx_decided:
	s_mov_b32 s2, 0x7bf4
	s_bitcmp1_b32 s2, s10
	s_cbranch_scc0 cvx_fullbar
	s_cmp_eq_u32 s101, 1
	s_cbranch_scc0 cvx_fullbar
	v_readlane_b32 s22, v253, 12
	v_readlane_b32 s23, v253, 13
	v_mov_b32_e32 v3, 0
	v_mov_b32_e32 v0, 1
	s_and_b32 s2, s89, 7
	s_lshl_b32 s2, s2, 7
	s_add_i32 s2, s2, 0x3600
	s_add_u32 s22, s22, s2
	s_addc_u32 s23, s23, 0
	global_atomic_add v1, v3, v0, s[22:23] sc0
	s_waitcnt vmcnt(0)
	v_readfirstlane_b32 s2, v1
	s_nop 0
	s_lshr_b32 s3, s2, 5
	s_add_i32 s3, s3, 1
	s_lshl_b32 s3, s3, 5
	s_add_i32 s2, s2, 1
	s_cmp_eq_u32 s2, s3
	s_cbranch_scc0 cvx_notlast
	s_cmp_eq_u32 s10, 8
	s_cbranch_scc0 cvx_notlast
cvx_lflush:
	buffer_wbl2 sc1
	s_waitcnt vmcnt(0)
	global_atomic_add v3, v0, s[22:23] offset:1024
	s_waitcnt vmcnt(0)
cvx_notlast:
	s_mov_b32 s2, 0

; __device__ __forceinline__ unsigned xb_ld(unsigned* p)              { return __hip_atomic_load(p, __ATOMIC_RELAXED, __HIP_MEMORY_SCOPE_AGENT); }
; __device__ __forceinline__ unsigned xb_add(unsigned* p, unsigned v) { return __hip_atomic_fetch_add(p, v, __ATOMIC_RELAXED, __HIP_MEMORY_SCOPE_AGENT); }
; #define XB_SPIN(cond, bar) do { unsigned _sp = 0; while (cond) { __builtin_amdgcn_s_sleep(1); \
;     if ((++_sp & 255u) == 0u) { if (xb_ld(&(bar)[XB_TMO])) break; if (_sp > XB_SPIN_CAP) { atomicAdd(&(bar)[XB_TMO], 1u); break; } } } } while (0)
; __device__ __forceinline__ void xcd_barrier(const XcdBarrier& b) {
;     asm volatile("s_waitcnt vmcnt(0)" ::: "memory");
;     __syncthreads();
;     if (threadIdx.x == 0) {
;         unsigned* bar = b.bar;
;         __builtin_amdgcn_s_waitcnt(0);
;         unsigned nloc = b.st[0], nx = b.st[1];
;         if (nloc == 0u) { xcd_barrier_complete(bar, b.x, nloc, nx); b.st[0] = nloc; b.st[1] = nx; }
;         const unsigned old = xb_add(&bar[XB_XSUB(b.x)], 1u);
;         const unsigned gen = old / nloc;
;         if (old + 1u == (gen + 1u) * nloc) {
;             __builtin_amdgcn_fence(__ATOMIC_RELEASE, "agent");
;             asm volatile("s_waitcnt vmcnt(0)" ::: "memory");
;             const unsigned og = xb_add(&bar[XB_TOP], 1u);
;             const unsigned tg = og / nx;
;             if (og + 1u == (tg + 1u) * nx) xb_add(&bar[XB_TOPGEN], 1u);
;             else XB_SPIN(xb_ld(&bar[XB_TOPGEN]) == tg, bar);
;             __builtin_amdgcn_fence(__ATOMIC_ACQUIRE, "agent");
;             xb_add(&bar[XB_XGEN(b.x)], 1u);
;             asm volatile("s_waitcnt vmcnt(0)" ::: "memory");
;         } else {
;             XB_SPIN(xb_ld(&bar[XB_XGEN(b.x)]) == gen, bar);
;             __builtin_amdgcn_fence(__ATOMIC_ACQUIRE, "agent");
;             asm volatile("s_waitcnt vmcnt(0)" ::: "memory");
;         }
;     }
;     __syncthreads();
; }
cvx_w71:
	s_cmp_eq_u32 s2, 7
	s_cbranch_scc1 cvx_done
	s_movk_i32 s3, 1
	s_add_u32 s22, s22, 0x480
	s_addc_u32 s23, s23, 0
	s_branch cvx_waitn
